# decw1: stack4 + decode K/V loop: exact counted vmcnt waits (29/25/24, K_B 31..24) in the steady trips instead of hipcc's path-insensitive vmcnt(5)/(4)/(1)/(0) that drained the load queue every trip
# speedup vs baseline: 1.0008x; 1.0008x over previous
.LBB0_387:
	s_sub_u32 s101, s17, 2
	s_cmp_lt_u32 s101, 11
	s_cselect_b32 s101, 1, 0
	s_waitcnt vmcnt(31)
	v_cvt_pk_bf16_f32 v0, v20, v21
	v_cvt_pk_bf16_f32 v1, v22, v23
	s_waitcnt vmcnt(30)
	v_cvt_pk_bf16_f32 v3, v24, v25
	ds_bpermute_b32 v180, v201, v0
	ds_bpermute_b32 v181, v201, v1
	ds_bpermute_b32 v182, v201, v3
	s_waitcnt vmcnt(29)
	v_cvt_pk_bf16_f32 v0, v28, v29
	v_cvt_pk_bf16_f32 v1, v30, v31
	s_waitcnt vmcnt(28)
	v_cvt_pk_bf16_f32 v3, v32, v33
	ds_bpermute_b32 v184, v201, v0
	ds_bpermute_b32 v185, v201, v1
	ds_bpermute_b32 v186, v201, v3
	s_waitcnt vmcnt(27)
	v_cvt_pk_bf16_f32 v0, v40, v41
	v_cvt_pk_bf16_f32 v1, v42, v43
	s_waitcnt vmcnt(26)
	v_cvt_pk_bf16_f32 v3, v48, v49
	v_cvt_pk_bf16_f32 v183, v26, v27
	v_cvt_pk_bf16_f32 v187, v34, v35
	v_cvt_pk_bf16_f32 v191, v50, v51
	ds_bpermute_b32 v188, v201, v0
	ds_bpermute_b32 v189, v201, v1
	ds_bpermute_b32 v190, v201, v3
	s_waitcnt vmcnt(25)
	v_cvt_pk_bf16_f32 v0, v56, v57
	v_cvt_pk_bf16_f32 v1, v58, v59
	s_waitcnt vmcnt(24)
	v_cvt_pk_bf16_f32 v3, v64, v65
	v_cvt_pk_bf16_f32 v195, v66, v67
	ds_bpermute_b32 v183, v201, v183
	ds_bpermute_b32 v187, v201, v187
	ds_bpermute_b32 v191, v201, v191
	ds_bpermute_b32 v192, v201, v0
	ds_bpermute_b32 v193, v201, v1
	ds_bpermute_b32 v194, v201, v3
	ds_bpermute_b32 v195, v201, v195
	s_cmp_lt_u32 s17, 14
	s_cselect_b64 s[44:45], -1, 0
	s_cmp_gt_u32 s17, 13
	s_cselect_b64 s[2:3], -1, 0
	s_and_b64 vcc, exec, s[2:3]
	v_lshlrev_b32_e32 v222, 2, v198
	s_cbranch_vccnz .LBB0_389
	s_cmp_lt_u32 s17, 6
	s_cselect_b32 vcc_lo, s16, s64
	s_ashr_i32 vcc_hi, vcc_lo, 31
	s_add_i32 s71, s78, 0xffffe000
	s_and_b32 s71, s71, 0xc000
	s_lshl_b64 vcc, vcc, 18
	s_add_u32 vcc_lo, s74, vcc_lo
	s_addc_u32 vcc_hi, s75, vcc_hi
	s_lshl_b32 s71, s71, 2
	s_add_u32 s71, vcc_lo, s71
	s_addc_u32 vcc_hi, vcc_hi, 0
	s_lshl_b32 vcc_lo, s62, 2
	s_add_u32 vcc_lo, s71, vcc_lo
	s_addc_u32 vcc_hi, vcc_hi, 0
	v_mov_b32_e32 v223, v2
	v_lshl_add_u64 v[0:1], vcc, 0, v[222:223]
	v_lshlrev_b32_e32 v20, 2, v200
	v_mov_b32_e32 v21, v2
	v_lshl_add_u64 v[0:1], v[0:1], 0, v[20:21]
	global_load_dwordx4 v[20:23], v[0:1], off
	global_load_dwordx4 v[24:27], v[0:1], off offset:64
	global_load_dwordx4 v[28:31], v[0:1], off offset:128
	global_load_dwordx4 v[32:35], v[0:1], off offset:192
	global_load_dwordx4 v[40:43], v[0:1], off offset:256
	global_load_dwordx4 v[48:51], v[0:1], off offset:320
	global_load_dwordx4 v[56:59], v[0:1], off offset:384
	global_load_dwordx4 v[64:67], v[0:1], off offset:448

.LBB0_391:
	v_sub_f32_e32 v0, v180, v216
	v_exp_f32_e32 v238, v0
	v_sub_f32_e32 v0, v181, v216
	v_exp_f32_e32 v239, v0
	v_sub_f32_e32 v0, v182, v216
	v_exp_f32_e32 v240, v0
	v_sub_f32_e32 v0, v183, v216
	v_exp_f32_e32 v241, v0
	s_cmp_eq_u32 s101, 0
	s_cbranch_scc1 .Ldw0_c
	s_waitcnt vmcnt(29)
	s_branch .Ldw0_j
.Ldw0_c:
	s_waitcnt vmcnt(21)
.Ldw0_j:
	v_cvt_pk_bf16_f32 v180, v36, v52
	s_cmp_eq_u32 s101, 0
	s_cbranch_scc1 .Ldw1_c
	s_waitcnt vmcnt(25)
	s_branch .Ldw1_j
.Ldw1_c:
	s_waitcnt vmcnt(5)
.Ldw1_j:
	v_cvt_pk_bf16_f32 v181, v116, v124
	v_mov_b32_e32 v182, v2
	v_mov_b32_e32 v183, v2
	v_cvt_pk_bf16_f32 v0, v238, v239
	v_cvt_pk_bf16_f32 v1, v240, v241
	v_mov_b32_e32 v3, v2
	s_andn2_b64 vcc, exec, s[44:45]
	v_lshlrev_b32_e32 v220, 2, v204
	v_mfma_f32_16x16x32_bf16 v[168:171], v[180:183], v[0:3], v[168:171]
	v_cvt_pk_bf16_f32 v180, v37, v53
	v_cvt_pk_bf16_f32 v181, v117, v125
	v_lshlrev_b32_e32 v218, 2, v196
	s_nop 0
	v_mfma_f32_16x16x32_bf16 v[172:175], v[180:183], v[0:3], v[172:175]
	v_cvt_pk_bf16_f32 v180, v38, v54
	v_cvt_pk_bf16_f32 v181, v118, v126
	s_nop 1
	v_mfma_f32_16x16x32_bf16 v[176:179], v[180:183], v[0:3], v[176:179]
	v_cvt_pk_bf16_f32 v180, v39, v55
	v_cvt_pk_bf16_f32 v181, v119, v127
	s_nop 1
	v_mfma_f32_16x16x32_bf16 v[164:167], v[180:183], v[0:3], v[164:167]
	v_cvt_pk_bf16_f32 v180, v44, v60
	s_cmp_eq_u32 s101, 0
	s_cbranch_scc1 .Ldw2_c
	s_waitcnt vmcnt(24)
	s_branch .Ldw2_j
.Ldw2_c:
	s_waitcnt vmcnt(4)
.Ldw2_j:
	v_cvt_pk_bf16_f32 v181, v120, v128
	s_nop 1
	v_mfma_f32_16x16x32_bf16 v[148:151], v[180:183], v[0:3], v[148:151]
	v_cvt_pk_bf16_f32 v180, v45, v61
	v_cvt_pk_bf16_f32 v181, v121, v129
	s_nop 1
	v_mfma_f32_16x16x32_bf16 v[152:155], v[180:183], v[0:3], v[152:155]
	v_cvt_pk_bf16_f32 v180, v46, v62
	v_cvt_pk_bf16_f32 v181, v122, v130
	s_nop 1
	v_mfma_f32_16x16x32_bf16 v[156:159], v[180:183], v[0:3], v[156:159]
	v_cvt_pk_bf16_f32 v180, v47, v63
	v_cvt_pk_bf16_f32 v181, v123, v131
	s_nop 1
	v_mfma_f32_16x16x32_bf16 v[160:163], v[180:183], v[0:3], v[160:163]
	s_cbranch_vccnz .LBB0_393
	s_cmp_lt_u32 s17, 6
	s_cselect_b32 s44, s16, s64
	s_ashr_i32 s45, s44, 31
	s_add_i32 s71, s78, 0xffffe000
	s_and_b32 s71, s71, 0xc000
	s_lshl_b64 s[44:45], s[44:45], 18
	s_add_u32 s44, s22, s44
	s_addc_u32 s45, s23, s45
	s_lshl_b32 s71, s71, 2
	s_add_u32 s44, s44, s71
	s_addc_u32 s45, s45, 0
	s_lshl_b32 s71, s62, 2
	s_add_u32 s44, s44, s71
	s_addc_u32 s45, s45, 0
	v_mov_b32_e32 v221, v2
	v_lshl_add_u64 v[0:1], s[44:45], 0, v[220:221]
	v_mov_b32_e32 v219, v2
	v_lshl_add_u64 v[0:1], v[0:1], 0, v[218:219]
	global_load_dwordx4 v[36:39], v[0:1], off
	global_load_dwordx4 v[44:47], v[0:1], off offset:256
	global_load_dwordx4 v[52:55], v[0:1], off offset:2048
	global_load_dwordx4 v[60:63], v[0:1], off offset:2304
	v_add_co_u32_e32 v0, vcc, s79, v0
	s_nop 1
	v_addc_co_u32_e32 v1, vcc, 0, v1, vcc
	global_load_dwordx4 v[116:119], v[0:1], off
	global_load_dwordx4 v[120:123], v[0:1], off offset:256
	global_load_dwordx4 v[124:127], v[0:1], off offset:2048
	global_load_dwordx4 v[128:131], v[0:1], off offset:2304
.LBB0_393:
	s_waitcnt vmcnt(31)
	v_cvt_pk_bf16_f32 v0, v68, v69
	v_cvt_pk_bf16_f32 v1, v70, v71
	s_waitcnt vmcnt(30)
	v_cvt_pk_bf16_f32 v3, v72, v73
	ds_bpermute_b32 v180, v201, v0
	ds_bpermute_b32 v181, v201, v1
	ds_bpermute_b32 v182, v201, v3
	s_waitcnt vmcnt(29)
	v_cvt_pk_bf16_f32 v0, v76, v77
	v_cvt_pk_bf16_f32 v1, v78, v79
	s_waitcnt vmcnt(28)
	v_cvt_pk_bf16_f32 v3, v80, v81
	v_cvt_pk_bf16_f32 v184, v82, v83
	ds_bpermute_b32 v188, v201, v0
	ds_bpermute_b32 v189, v201, v1
	ds_bpermute_b32 v190, v201, v3
	s_waitcnt vmcnt(27)
	v_cvt_pk_bf16_f32 v0, v88, v89
	v_cvt_pk_bf16_f32 v1, v90, v91
	s_waitcnt vmcnt(26)
	v_cvt_pk_bf16_f32 v3, v96, v97
	v_cvt_pk_bf16_f32 v183, v74, v75
	ds_bpermute_b32 v191, v201, v184
	v_cvt_pk_bf16_f32 v184, v98, v99
	ds_bpermute_b32 v192, v201, v0
	ds_bpermute_b32 v193, v201, v1
	ds_bpermute_b32 v194, v201, v3
	s_waitcnt vmcnt(25)
	v_cvt_pk_bf16_f32 v0, v104, v105
	v_cvt_pk_bf16_f32 v1, v106, v107
	s_waitcnt vmcnt(24)
	v_cvt_pk_bf16_f32 v3, v112, v113
	v_cvt_pk_bf16_f32 v187, v114, v115
	ds_bpermute_b32 v183, v201, v183
	ds_bpermute_b32 v195, v201, v184
	ds_bpermute_b32 v184, v201, v0
	ds_bpermute_b32 v185, v201, v1
	ds_bpermute_b32 v186, v201, v3
	ds_bpermute_b32 v187, v201, v187
	s_cmp_lt_u32 s17, 13
	s_cselect_b64 s[44:45], -1, 0
	s_cmp_gt_u32 s17, 12
	s_cbranch_scc1 .LBB0_395
	s_cmp_lt_u32 s17, 5
	s_cselect_b32 vcc_lo, s16, s64
	s_ashr_i32 vcc_hi, vcc_lo, 31
	s_and_b32 s71, s78, 0xe000
	s_lshl_b64 vcc, vcc, 18
	s_add_u32 vcc_lo, s74, vcc_lo
	s_addc_u32 vcc_hi, s75, vcc_hi
	s_lshl_b32 s71, s71, 2
	s_add_u32 s71, vcc_lo, s71
	s_addc_u32 vcc_hi, vcc_hi, 0
	s_lshl_b32 vcc_lo, s62, 2
	s_add_u32 vcc_lo, s71, vcc_lo
	s_addc_u32 vcc_hi, vcc_hi, 0
	v_mov_b32_e32 v223, v2
	v_lshl_add_u64 v[0:1], vcc, 0, v[222:223]
	v_lshlrev_b32_e32 v68, 2, v200
	v_mov_b32_e32 v69, v2
	v_lshl_add_u64 v[0:1], v[0:1], 0, v[68:69]
	global_load_dwordx4 v[68:71], v[0:1], off
	global_load_dwordx4 v[72:75], v[0:1], off offset:64
	global_load_dwordx4 v[76:79], v[0:1], off offset:128
	global_load_dwordx4 v[80:83], v[0:1], off offset:192
	global_load_dwordx4 v[88:91], v[0:1], off offset:256
	global_load_dwordx4 v[96:99], v[0:1], off offset:320
	global_load_dwordx4 v[104:107], v[0:1], off offset:384
	global_load_dwordx4 v[112:115], v[0:1], off offset:448

.LBB0_397:
	v_sub_f32_e32 v0, v180, v216
	v_exp_f32_e32 v180, v0
	v_sub_f32_e32 v0, v181, v216
	v_exp_f32_e32 v181, v0
	v_sub_f32_e32 v0, v182, v216
	v_exp_f32_e32 v182, v0
	v_sub_f32_e32 v0, v183, v216
	v_exp_f32_e32 v183, v0
	s_cmp_eq_u32 s101, 0
	s_cbranch_scc1 .Ldw3_c
	s_waitcnt vmcnt(29)
.Ldw3_c:
	v_cvt_pk_bf16_f32 v184, v84, v100
	s_cmp_eq_u32 s101, 0
	s_cbranch_scc1 .Ldw4_c
	s_waitcnt vmcnt(25)
	s_branch .Ldw4_j

.Ldw4_j:
	v_cvt_pk_bf16_f32 v185, v132, v140
	v_mov_b32_e32 v186, v2
	v_mov_b32_e32 v187, v2
	v_cvt_pk_bf16_f32 v0, v180, v181
	v_cvt_pk_bf16_f32 v1, v182, v183
	v_mov_b32_e32 v3, v2
	s_andn2_b64 vcc, exec, s[44:45]
	s_nop 0
	v_mfma_f32_16x16x32_bf16 v[168:171], v[184:187], v[0:3], v[168:171]
	v_cvt_pk_bf16_f32 v184, v85, v101
	v_cvt_pk_bf16_f32 v185, v133, v141
	s_nop 1
	v_mfma_f32_16x16x32_bf16 v[172:175], v[184:187], v[0:3], v[172:175]
	v_cvt_pk_bf16_f32 v184, v86, v102
	v_cvt_pk_bf16_f32 v185, v134, v142
	s_nop 1
	v_mfma_f32_16x16x32_bf16 v[176:179], v[184:187], v[0:3], v[176:179]
	v_cvt_pk_bf16_f32 v184, v87, v103
	v_cvt_pk_bf16_f32 v185, v135, v143
	s_nop 1
	v_mfma_f32_16x16x32_bf16 v[164:167], v[184:187], v[0:3], v[164:167]
	v_cvt_pk_bf16_f32 v184, v92, v108
	s_cmp_eq_u32 s101, 0
	s_cbranch_scc1 .Ldw5_c
	s_waitcnt vmcnt(24)
	s_branch .Ldw5_j

.Ldw5_j:
	v_cvt_pk_bf16_f32 v185, v136, v144
	s_nop 1
	v_mfma_f32_16x16x32_bf16 v[148:151], v[184:187], v[0:3], v[148:151]
	v_cvt_pk_bf16_f32 v184, v93, v109
	v_cvt_pk_bf16_f32 v185, v137, v145
	s_nop 1
	v_mfma_f32_16x16x32_bf16 v[152:155], v[184:187], v[0:3], v[152:155]
	v_cvt_pk_bf16_f32 v184, v94, v110
	v_cvt_pk_bf16_f32 v185, v138, v146
	s_nop 1
	v_mfma_f32_16x16x32_bf16 v[156:159], v[184:187], v[0:3], v[156:159]
	v_cvt_pk_bf16_f32 v184, v95, v111
	v_cvt_pk_bf16_f32 v185, v139, v147
	s_nop 1
	v_mfma_f32_16x16x32_bf16 v[160:163], v[184:187], v[0:3], v[160:163]
	s_cbranch_vccnz .LBB0_386
	s_cmp_lt_u32 s17, 5
	s_cselect_b32 s44, s16, s64
	s_ashr_i32 s45, s44, 31
	s_and_b32 s71, s78, 0xe000
	s_lshl_b64 s[44:45], s[44:45], 18
	s_add_u32 s44, s22, s44
	s_addc_u32 s45, s23, s45
	s_lshl_b32 s71, s71, 2
	s_add_u32 s44, s44, s71
	s_addc_u32 s45, s45, 0
	s_lshl_b32 s71, s62, 2
	s_add_u32 s44, s44, s71
	s_addc_u32 s45, s45, 0
	v_mov_b32_e32 v221, v2
	v_lshl_add_u64 v[0:1], s[44:45], 0, v[220:221]
	v_mov_b32_e32 v219, v2
	v_lshl_add_u64 v[0:1], v[0:1], 0, v[218:219]
	global_load_dwordx4 v[84:87], v[0:1], off
	global_load_dwordx4 v[92:95], v[0:1], off offset:256
	global_load_dwordx4 v[100:103], v[0:1], off offset:2048
	global_load_dwordx4 v[108:111], v[0:1], off offset:2304
	v_add_co_u32_e32 v0, vcc, 0x1000, v0
	s_nop 1
	v_addc_co_u32_e32 v1, vcc, 0, v1, vcc
	global_load_dwordx4 v[132:135], v[0:1], off
	global_load_dwordx4 v[136:139], v[0:1], off offset:256
	global_load_dwordx4 v[140:143], v[0:1], off offset:2048
	global_load_dwordx4 v[144:147], v[0:1], off offset:2304
	s_branch .LBB0_386
